# prompt attention epilogue: 8 dwordx2 output stores paired into 4 dwordx4 via permlane32_swap (32 contiguous bytes per row per store), on top of the stacked file
# speedup vs baseline: 1.0081x; 1.0006x over previous
; #define GAS __attribute__((address_space(1)))
; DI unsigned pk2(float lo, float hi) { return f2bf(lo) | (f2bf(hi) << 16); }
; DI float xhalf_sum(float v) { auto rr = __builtin_amdgcn_permlane32_swap(__float_as_uint(v), __float_as_uint(v), false, false); return __uint_as_float(rr[0]) + __uint_as_float(rr[1]); }
; template <int ABL> DI void prompt_unit(LAS unsigned char* lds, const bf16* QBP, const unsigned char* KTH, const unsigned char* KTR, bf16* OMP, int b, int hd, int j, int tid, int wave, int lane) {
;     ...
;     const float inv = 1.f / (o[2][0] + xhalf_sum(lrun));
;     bf16* op = OMP + (size_t)(row0 + r) * 1024 + hd * 64 + 4 * h;
; #pragma unroll
;     for (int d = 0; d < 2; ++d)
; #pragma unroll
;         for (int g = 0; g < 4; ++g)
;             *(GAS v2u*)(op + 32 * d + 8 * g) = (v2u){pk2(o[d][4 * g] * inv, o[d][4 * g + 1] * inv), pk2(o[d][4 * g + 2] * inv, o[d][4 * g + 3] * inv)};
.LBB0_1202:
	s_setprio 0
	v_mov_b32_e32 v2, v98
	s_nop 1
	v_permlane32_swap_b32_e32 v98, v2
	v_add_f32_e32 v2, v98, v2
	v_add_f32_e32 v2, v82, v2
	v_div_scale_f32 v3, s[38:39], v2, v2, 1.0
	v_rcp_f32_e32 v4, v3
	s_lshl_b32 s78, s52, 7
	v_mov_b32_e32 v165, v159
	s_waitcnt vmcnt(0)
	v_fma_f32 v5, -v3, v4, 1.0
	v_fmac_f32_e32 v4, v5, v4
	v_div_scale_f32 v5, vcc, 1.0, v2, 1.0
	v_mul_f32_e32 v6, v5, v4
	v_fma_f32 v7, -v3, v6, v5
	v_fmac_f32_e32 v6, v7, v4
	v_fma_f32 v3, -v3, v6, v5
	v_div_fmas_f32 v3, v3, v4, v6
	v_div_fixup_f32 v2, v3, v2, 1.0
	v_mov_b32_e32 v6, v50
	v_mov_b32_e32 v7, v52
	v_pk_mul_f32 v[6:7], v[6:7], v[2:3] op_sel_hi:[1,0]
	v_mov_b32_e32 v52, v51
	v_pk_mul_f32 v[8:9], v[52:53], v[2:3] op_sel_hi:[1,0]
	v_and_b32_sdwa v3, v7, v202 dst_sel:DWORD dst_unused:UNUSED_PAD src0_sel:WORD_1 src1_sel:DWORD
	v_and_b32_sdwa v10, v6, v202 dst_sel:DWORD dst_unused:UNUSED_PAD src0_sel:WORD_1 src1_sel:DWORD
	v_lshlrev_b64 v[4:5], 11, v[158:159]
	v_add3_u32 v6, v6, v10, s54
	v_add3_u32 v3, v7, v3, s54
	v_and_b32_sdwa v7, v9, v202 dst_sel:DWORD dst_unused:UNUSED_PAD src0_sel:WORD_1 src1_sel:DWORD
	v_and_b32_sdwa v10, v8, v202 dst_sel:DWORD dst_unused:UNUSED_PAD src0_sel:WORD_1 src1_sel:DWORD
	v_lshl_add_u64 v[4:5], s[76:77], 0, v[4:5]
	v_add3_u32 v7, v9, v7, s54
	v_add3_u32 v8, v8, v10, s54
	v_lshl_add_u64 v[4:5], v[4:5], 0, s[78:79]
	v_and_b32_e32 v7, 0xffff0000, v7
	v_and_b32_e32 v8, 0xffff0000, v8
	v_lshl_add_u64 v[4:5], v[4:5], 0, v[164:165]
	v_or_b32_sdwa v7, v7, v3 dst_sel:DWORD dst_unused:UNUSED_PAD src0_sel:DWORD src1_sel:WORD_1
	v_or_b32_sdwa v6, v8, v6 dst_sel:DWORD dst_unused:UNUSED_PAD src0_sel:DWORD src1_sel:WORD_1
	s_waitcnt vmcnt(0) lgkmcnt(0)
	s_barrier
	v_mov_b32_e32 v50, v6
	v_mov_b32_e32 v51, v7
	v_mov_b32_e32 v6, v54
	v_mov_b32_e32 v7, v56
	v_pk_mul_f32 v[6:7], v[6:7], v[2:3] op_sel_hi:[1,0]
	v_mov_b32_e32 v56, v55
	v_pk_mul_f32 v[8:9], v[56:57], v[2:3] op_sel_hi:[1,0]
	v_and_b32_sdwa v3, v7, v202 dst_sel:DWORD dst_unused:UNUSED_PAD src0_sel:WORD_1 src1_sel:DWORD
	v_and_b32_sdwa v10, v6, v202 dst_sel:DWORD dst_unused:UNUSED_PAD src0_sel:WORD_1 src1_sel:DWORD
	v_add3_u32 v6, v6, v10, s54
	v_add3_u32 v3, v7, v3, s54
	v_and_b32_sdwa v7, v9, v202 dst_sel:DWORD dst_unused:UNUSED_PAD src0_sel:WORD_1 src1_sel:DWORD
	v_and_b32_sdwa v10, v8, v202 dst_sel:DWORD dst_unused:UNUSED_PAD src0_sel:WORD_1 src1_sel:DWORD
	v_add3_u32 v7, v9, v7, s54
	v_add3_u32 v8, v8, v10, s54
	v_and_b32_e32 v7, 0xffff0000, v7
	v_and_b32_e32 v8, 0xffff0000, v8
	v_or_b32_sdwa v7, v7, v3 dst_sel:DWORD dst_unused:UNUSED_PAD src0_sel:DWORD src1_sel:WORD_1
	v_or_b32_sdwa v6, v8, v6 dst_sel:DWORD dst_unused:UNUSED_PAD src0_sel:DWORD src1_sel:WORD_1
	v_mov_b32_e32 v52, v6
	v_mov_b32_e32 v53, v7
	v_mbcnt_lo_u32_b32 v54, -1, 0
	v_mbcnt_hi_u32_b32 v54, -1, v54
	v_lshrrev_b32_e32 v54, 5, v54
	v_lshlrev_b32_e32 v54, 3, v54
	v_mov_b32_e32 v55, 0
	v_lshl_add_u64 v[4:5], v[4:5], 0, v[54:55]
	v_permlane32_swap_b32_e32 v50, v52
	v_permlane32_swap_b32_e32 v51, v53
	global_store_dwordx4 v[4:5], v[50:53], off
	v_mov_b32_e32 v6, v58
	v_mov_b32_e32 v7, v60
	v_pk_mul_f32 v[6:7], v[6:7], v[2:3] op_sel_hi:[1,0]
	v_mov_b32_e32 v60, v59
	v_pk_mul_f32 v[8:9], v[60:61], v[2:3] op_sel_hi:[1,0]
	v_and_b32_sdwa v3, v7, v202 dst_sel:DWORD dst_unused:UNUSED_PAD src0_sel:WORD_1 src1_sel:DWORD
	v_and_b32_sdwa v10, v6, v202 dst_sel:DWORD dst_unused:UNUSED_PAD src0_sel:WORD_1 src1_sel:DWORD
	v_add3_u32 v6, v6, v10, s54
	v_add3_u32 v3, v7, v3, s54
	v_and_b32_sdwa v7, v9, v202 dst_sel:DWORD dst_unused:UNUSED_PAD src0_sel:WORD_1 src1_sel:DWORD
	v_and_b32_sdwa v10, v8, v202 dst_sel:DWORD dst_unused:UNUSED_PAD src0_sel:WORD_1 src1_sel:DWORD
	v_add3_u32 v7, v9, v7, s54
	v_add3_u32 v8, v8, v10, s54
	v_and_b32_e32 v7, 0xffff0000, v7
	v_and_b32_e32 v8, 0xffff0000, v8
	v_or_b32_sdwa v7, v7, v3 dst_sel:DWORD dst_unused:UNUSED_PAD src0_sel:DWORD src1_sel:WORD_1
	v_or_b32_sdwa v6, v8, v6 dst_sel:DWORD dst_unused:UNUSED_PAD src0_sel:DWORD src1_sel:WORD_1
	v_mov_b32_e32 v58, v6
	v_mov_b32_e32 v59, v7
	v_mov_b32_e32 v6, v62
	v_mov_b32_e32 v7, v64
	v_pk_mul_f32 v[6:7], v[6:7], v[2:3] op_sel_hi:[1,0]
	v_mov_b32_e32 v64, v63
	v_pk_mul_f32 v[8:9], v[64:65], v[2:3] op_sel_hi:[1,0]
	v_and_b32_sdwa v3, v7, v202 dst_sel:DWORD dst_unused:UNUSED_PAD src0_sel:WORD_1 src1_sel:DWORD
	v_and_b32_sdwa v10, v6, v202 dst_sel:DWORD dst_unused:UNUSED_PAD src0_sel:WORD_1 src1_sel:DWORD
	v_add3_u32 v6, v6, v10, s54
	v_add3_u32 v3, v7, v3, s54
	v_and_b32_sdwa v7, v9, v202 dst_sel:DWORD dst_unused:UNUSED_PAD src0_sel:WORD_1 src1_sel:DWORD
	v_and_b32_sdwa v10, v8, v202 dst_sel:DWORD dst_unused:UNUSED_PAD src0_sel:WORD_1 src1_sel:DWORD
	v_add3_u32 v7, v9, v7, s54
	v_add3_u32 v8, v8, v10, s54
	v_and_b32_e32 v7, 0xffff0000, v7
; #define GAS __attribute__((address_space(1)))
; DI unsigned pk2(float lo, float hi) { return f2bf(lo) | (f2bf(hi) << 16); }
; DI float xhalf_sum(float v) { auto rr = __builtin_amdgcn_permlane32_swap(__float_as_uint(v), __float_as_uint(v), false, false); return __uint_as_float(rr[0]) + __uint_as_float(rr[1]); }
; template <int ABL> DI void prompt_unit(LAS unsigned char* lds, const bf16* QBP, const unsigned char* KTH, const unsigned char* KTR, bf16* OMP, int b, int hd, int j, int tid, int wave, int lane) {
;     ...
;     const float inv = 1.f / (o[2][0] + xhalf_sum(lrun));
;     bf16* op = OMP + (size_t)(row0 + r) * 1024 + hd * 64 + 4 * h;
; #pragma unroll
;     for (int d = 0; d < 2; ++d)
; #pragma unroll
;         for (int g = 0; g < 4; ++g)
;             *(GAS v2u*)(op + 32 * d + 8 * g) = (v2u){pk2(o[d][4 * g] * inv, o[d][4 * g + 1] * inv), pk2(o[d][4 * g + 2] * inv, o[d][4 * g + 3] * inv)};
; template <int MODE, int VAR> DI void mixer_phase(const Ptrs& P, LAS unsigned char* lds, volatile LAS unsigned* MISC, gu32* ctl, int tid, int wave, int lane) {
;     ...
;         if (tid == 0) MISC[0] = nx_; __syncthreads(); it = (int)MISC[0]; __syncthreads(); it = __builtin_amdgcn_readfirstlane(it); }
	v_and_b32_e32 v8, 0xffff0000, v8
	v_or_b32_sdwa v7, v7, v3 dst_sel:DWORD dst_unused:UNUSED_PAD src0_sel:DWORD src1_sel:WORD_1
	v_or_b32_sdwa v6, v8, v6 dst_sel:DWORD dst_unused:UNUSED_PAD src0_sel:DWORD src1_sel:WORD_1
	v_mov_b32_e32 v60, v6
	v_mov_b32_e32 v61, v7
	s_nop 1
	v_permlane32_swap_b32_e32 v58, v60
	v_permlane32_swap_b32_e32 v59, v61
	global_store_dwordx4 v[4:5], v[58:61], off offset:32
	v_mov_b32_e32 v6, v66
	v_mov_b32_e32 v7, v68
	v_pk_mul_f32 v[6:7], v[6:7], v[2:3] op_sel_hi:[1,0]
	v_mov_b32_e32 v68, v67
	v_pk_mul_f32 v[8:9], v[68:69], v[2:3] op_sel_hi:[1,0]
	v_and_b32_sdwa v3, v7, v202 dst_sel:DWORD dst_unused:UNUSED_PAD src0_sel:WORD_1 src1_sel:DWORD
	v_and_b32_sdwa v10, v6, v202 dst_sel:DWORD dst_unused:UNUSED_PAD src0_sel:WORD_1 src1_sel:DWORD
	v_add3_u32 v6, v6, v10, s54
	v_add3_u32 v3, v7, v3, s54
	v_and_b32_sdwa v7, v9, v202 dst_sel:DWORD dst_unused:UNUSED_PAD src0_sel:WORD_1 src1_sel:DWORD
	v_and_b32_sdwa v10, v8, v202 dst_sel:DWORD dst_unused:UNUSED_PAD src0_sel:WORD_1 src1_sel:DWORD
	v_add3_u32 v7, v9, v7, s54
	v_add3_u32 v8, v8, v10, s54
	v_and_b32_e32 v7, 0xffff0000, v7
	v_and_b32_e32 v8, 0xffff0000, v8
	v_or_b32_sdwa v7, v7, v3 dst_sel:DWORD dst_unused:UNUSED_PAD src0_sel:DWORD src1_sel:WORD_1
	v_or_b32_sdwa v6, v8, v6 dst_sel:DWORD dst_unused:UNUSED_PAD src0_sel:DWORD src1_sel:WORD_1
	v_mov_b32_e32 v66, v6
	v_mov_b32_e32 v67, v7
	v_mov_b32_e32 v6, v70
	v_mov_b32_e32 v7, v72
	v_pk_mul_f32 v[6:7], v[6:7], v[2:3] op_sel_hi:[1,0]
	v_mov_b32_e32 v72, v71
	v_pk_mul_f32 v[8:9], v[72:73], v[2:3] op_sel_hi:[1,0]
	v_and_b32_sdwa v3, v7, v202 dst_sel:DWORD dst_unused:UNUSED_PAD src0_sel:WORD_1 src1_sel:DWORD
	v_and_b32_sdwa v10, v6, v202 dst_sel:DWORD dst_unused:UNUSED_PAD src0_sel:WORD_1 src1_sel:DWORD
	v_add3_u32 v6, v6, v10, s54
	v_add3_u32 v3, v7, v3, s54
	v_and_b32_sdwa v7, v9, v202 dst_sel:DWORD dst_unused:UNUSED_PAD src0_sel:WORD_1 src1_sel:DWORD
	v_and_b32_sdwa v10, v8, v202 dst_sel:DWORD dst_unused:UNUSED_PAD src0_sel:WORD_1 src1_sel:DWORD
	v_add3_u32 v7, v9, v7, s54
	v_add3_u32 v8, v8, v10, s54
	v_and_b32_e32 v7, 0xffff0000, v7
	v_and_b32_e32 v8, 0xffff0000, v8
	v_or_b32_sdwa v7, v7, v3 dst_sel:DWORD dst_unused:UNUSED_PAD src0_sel:DWORD src1_sel:WORD_1
	v_or_b32_sdwa v6, v8, v6 dst_sel:DWORD dst_unused:UNUSED_PAD src0_sel:DWORD src1_sel:WORD_1
	v_mov_b32_e32 v68, v6
	v_mov_b32_e32 v69, v7
	s_nop 1
	v_permlane32_swap_b32_e32 v66, v68
	v_permlane32_swap_b32_e32 v67, v69
	global_store_dwordx4 v[4:5], v[66:69], off offset:64
	v_mov_b32_e32 v6, v74
	v_mov_b32_e32 v7, v76
	v_pk_mul_f32 v[6:7], v[6:7], v[2:3] op_sel_hi:[1,0]
	v_mov_b32_e32 v76, v75
	v_pk_mul_f32 v[8:9], v[76:77], v[2:3] op_sel_hi:[1,0]
	v_and_b32_sdwa v3, v7, v202 dst_sel:DWORD dst_unused:UNUSED_PAD src0_sel:WORD_1 src1_sel:DWORD
	v_and_b32_sdwa v10, v6, v202 dst_sel:DWORD dst_unused:UNUSED_PAD src0_sel:WORD_1 src1_sel:DWORD
	v_add3_u32 v6, v6, v10, s54
	v_add3_u32 v3, v7, v3, s54
	v_and_b32_sdwa v7, v9, v202 dst_sel:DWORD dst_unused:UNUSED_PAD src0_sel:WORD_1 src1_sel:DWORD
	v_and_b32_sdwa v10, v8, v202 dst_sel:DWORD dst_unused:UNUSED_PAD src0_sel:WORD_1 src1_sel:DWORD
	v_add3_u32 v7, v9, v7, s54
	v_add3_u32 v8, v8, v10, s54
	v_and_b32_e32 v7, 0xffff0000, v7
	v_and_b32_e32 v8, 0xffff0000, v8
	v_or_b32_sdwa v7, v7, v3 dst_sel:DWORD dst_unused:UNUSED_PAD src0_sel:DWORD src1_sel:WORD_1
	v_or_b32_sdwa v6, v8, v6 dst_sel:DWORD dst_unused:UNUSED_PAD src0_sel:DWORD src1_sel:WORD_1
	v_mov_b32_e32 v74, v6
	v_mov_b32_e32 v75, v7
	v_mov_b32_e32 v6, v78
	v_mov_b32_e32 v7, v80
	v_pk_mul_f32 v[6:7], v[6:7], v[2:3] op_sel_hi:[1,0]
	v_mov_b32_e32 v80, v79
	v_pk_mul_f32 v[2:3], v[80:81], v[2:3] op_sel_hi:[1,0]
	v_and_b32_sdwa v8, v7, v202 dst_sel:DWORD dst_unused:UNUSED_PAD src0_sel:WORD_1 src1_sel:DWORD
	v_and_b32_sdwa v9, v6, v202 dst_sel:DWORD dst_unused:UNUSED_PAD src0_sel:WORD_1 src1_sel:DWORD
	v_add3_u32 v6, v6, v9, s54
	v_add3_u32 v7, v7, v8, s54
	v_and_b32_sdwa v8, v3, v202 dst_sel:DWORD dst_unused:UNUSED_PAD src0_sel:WORD_1 src1_sel:DWORD
	v_and_b32_sdwa v9, v2, v202 dst_sel:DWORD dst_unused:UNUSED_PAD src0_sel:WORD_1 src1_sel:DWORD
	v_add3_u32 v3, v3, v8, s54
	v_add3_u32 v2, v2, v9, s54
	v_and_b32_e32 v3, 0xffff0000, v3
	v_and_b32_e32 v2, 0xffff0000, v2
	v_or_b32_sdwa v3, v3, v7 dst_sel:DWORD dst_unused:UNUSED_PAD src0_sel:DWORD src1_sel:WORD_1
	v_or_b32_sdwa v2, v2, v6 dst_sel:DWORD dst_unused:UNUSED_PAD src0_sel:DWORD src1_sel:WORD_1
	v_mov_b32_e32 v76, v2
	v_mov_b32_e32 v77, v3
	s_nop 1
	v_permlane32_swap_b32_e32 v74, v76
	v_permlane32_swap_b32_e32 v75, v77
	global_store_dwordx4 v[4:5], v[74:77], off offset:96
	s_and_saveexec_b64 s[38:39], s[2:3]
	s_cbranch_execz .LBB0_1076
	v_mov_b32_e32 v2, s55
	ds_write_b32 v2, v203
	s_branch .LBB0_1076
